# gate byte scratch re-laid out per lane (both 8-byte groups adjacent): gate epilogue stores and merge epilogue gate loads become one 16-byte access each
# baseline (speedup 1.0000x reference)
; __device__ __forceinline__ float rstd16(const float* part, int row) {
;     const f32x4* p = (const f32x4*)(part + (size_t)row * 16); const f32x4 a = p[0], b = p[1], c = p[2], d = p[3];
;     const float s = ((a.x + a.y) + (a.z + a.w)) + ((b.x + b.y) + (b.z + b.w)) + ((c.x + c.y) + (c.z + c.w)) + ((d.x + d.y) + (d.z + d.w));
;     return rsqrtf(s * (1.f / 1024.f) + 1e-6f);
.LBB0_1578:
	v_lshl_or_b32 v164, s19, 8, v194
	v_ashrrev_i32_e32 v165, 31, v164
	v_lshl_add_u64 v[28:29], v[164:165], 2, s[16:17]
	global_load_dwordx4 v[40:43], v[28:29], off offset:16
	global_load_dwordx4 v[44:47], v[28:29], off
	global_load_dwordx4 v[24:27], v[28:29], off offset:528
	s_nop 0
	global_load_dwordx4 v[28:31], v[28:29], off offset:512
	v_lshl_add_u32 v166, s18, 8, v192
	v_ashrrev_i32_e32 v167, 31, v166
	v_readlane_b32 s26, v254, 8
	v_lshlrev_b64 v[196:197], 6, v[166:167]
	v_readlane_b32 s27, v254, 9
	s_mov_b32 s29, 0x800000
	s_mov_b32 s36, 0x437f0000
	v_lshl_add_u64 v[208:209], s[26:27], 0, v[196:197]
	v_mbcnt_lo_u32_b32 v198, -1, 0
	v_mbcnt_hi_u32_b32 v198, -1, v198
	v_and_b32_e32 v199, 48, v198
	v_xor_b32_e32 v210, 16, v198
	v_xor_b32_e32 v211, 32, v198
	v_lshlrev_b32_e32 v210, 2, v210
	v_lshlrev_b32_e32 v211, 2, v211
	v_mov_b32_e32 v198, v166
	v_lshl_or_b32 v198, v198, 6, v199
	global_load_dwordx4 v[200:203], v198, s[26:27]
	v_add_u32_e32 v198, 16, v166
	v_lshl_or_b32 v198, v198, 6, v199
	global_load_dwordx4 v[204:207], v198, s[26:27]
	v_add_u32_e32 v198, 32, v166
	v_lshl_or_b32 v198, v198, 6, v199
	global_load_dwordx4 v[212:215], v198, s[26:27]
	v_add_u32_e32 v198, 48, v166
	v_lshl_or_b32 v198, v198, 6, v199
	global_load_dwordx4 v[216:219], v198, s[26:27]
	v_add_u32_e32 v198, 128, v166
	v_lshl_or_b32 v198, v198, 6, v199
	global_load_dwordx4 v[220:223], v198, s[26:27]
	v_add_u32_e32 v198, 144, v166
	v_lshl_or_b32 v198, v198, 6, v199
	global_load_dwordx4 v[224:227], v198, s[26:27]
	v_add_u32_e32 v198, 160, v166
	v_lshl_or_b32 v198, v198, 6, v199
	global_load_dwordx4 v[228:231], v198, s[26:27]
	v_add_u32_e32 v198, 176, v166
	v_lshl_or_b32 v198, v198, 6, v199
	global_load_dwordx4 v[232:235], v198, s[26:27]
	s_waitcnt vmcnt(0)
	v_pk_add_f32 v[200:201], v[200:201], v[202:203]
	v_pk_add_f32 v[204:205], v[204:205], v[206:207]
	v_pk_add_f32 v[212:213], v[212:213], v[214:215]
	v_pk_add_f32 v[216:217], v[216:217], v[218:219]
	v_pk_add_f32 v[220:221], v[220:221], v[222:223]
	v_pk_add_f32 v[224:225], v[224:225], v[226:227]
	v_pk_add_f32 v[228:229], v[228:229], v[230:231]
	v_pk_add_f32 v[232:233], v[232:233], v[234:235]
	v_add_f32_e32 v200, v200, v201
	v_add_f32_e32 v204, v204, v205
	v_add_f32_e32 v212, v212, v213
	v_add_f32_e32 v216, v216, v217
	v_add_f32_e32 v220, v220, v221
	v_add_f32_e32 v224, v224, v225
	v_add_f32_e32 v228, v228, v229
	v_add_f32_e32 v232, v232, v233
	ds_bpermute_b32 v201, v210, v200
	ds_bpermute_b32 v205, v210, v204
	ds_bpermute_b32 v213, v210, v212
	ds_bpermute_b32 v217, v210, v216
	ds_bpermute_b32 v221, v210, v220
	ds_bpermute_b32 v225, v210, v224
	ds_bpermute_b32 v229, v210, v228
	ds_bpermute_b32 v233, v210, v232
	s_waitcnt lgkmcnt(0)
	v_add_f32_e32 v200, v200, v201
	v_add_f32_e32 v204, v204, v205
	v_add_f32_e32 v212, v212, v213
	v_add_f32_e32 v216, v216, v217
	v_add_f32_e32 v220, v220, v221
	v_add_f32_e32 v224, v224, v225
	v_add_f32_e32 v228, v228, v229
	v_add_f32_e32 v232, v232, v233
	ds_bpermute_b32 v201, v211, v200
	ds_bpermute_b32 v205, v211, v204
	ds_bpermute_b32 v213, v211, v212
	ds_bpermute_b32 v217, v211, v216
	ds_bpermute_b32 v221, v211, v220
	ds_bpermute_b32 v225, v211, v224
	ds_bpermute_b32 v229, v211, v228
	ds_bpermute_b32 v233, v211, v232
	s_waitcnt lgkmcnt(0)
	v_add_f32_e32 v200, v200, v201
	v_add_f32_e32 v204, v204, v205
	v_add_f32_e32 v212, v212, v213
	v_add_f32_e32 v216, v216, v217
	v_add_f32_e32 v220, v220, v221
	v_add_f32_e32 v224, v224, v225
	v_add_f32_e32 v228, v228, v229
	v_add_f32_e32 v232, v232, v233
	v_fmamk_f32 v200, v200, 0x3a800000, v171
	v_fmamk_f32 v204, v204, 0x3a800000, v171
	v_fmamk_f32 v212, v212, 0x3a800000, v171
	v_fmamk_f32 v216, v216, 0x3a800000, v171
	v_fmamk_f32 v220, v220, 0x3a800000, v171
	v_fmamk_f32 v224, v224, 0x3a800000, v171
	v_fmamk_f32 v228, v228, 0x3a800000, v171
	v_fmamk_f32 v232, v232, 0x3a800000, v171
	v_rsq_f32_e32 v203, v200
	v_rsq_f32_e32 v207, v204
	v_rsq_f32_e32 v215, v212
	v_rsq_f32_e32 v219, v216
	v_rsq_f32_e32 v223, v220
	v_rsq_f32_e32 v227, v224
	v_rsq_f32_e32 v231, v228
	v_rsq_f32_e32 v235, v232
	s_nop 0
	s_movk_i32 s28, 0xc00
	s_nop 0
	s_nop 0
	s_nop 0
	s_nop 0
	v_mov_b32_e32 v167, v203
	v_fma_f32 v136, v136, v167, v40
	v_mul_f32_e32 v136, 0xbfb8aa3b, v136
	v_fma_f32 v140, v140, v167, v44
	v_exp_f32_e32 v136, v136
	v_mul_f32_e32 v140, 0xbfb8aa3b, v140
	v_fma_f32 v138, v138, v167, v42
	v_exp_f32_e32 v140, v140
	v_mul_f32_e32 v138, 0xbfb8aa3b, v138
	v_exp_f32_e32 v138, v138
	v_add_f32_e32 v136, 1.0, v136
	v_rcp_f32_e32 v197, v136
	v_fma_f32 v136, v141, v167, v45
	v_fma_f32 v137, v137, v167, v41
	v_add_f32_e32 v140, 1.0, v140
	v_mul_f32_e32 v136, 0xbfb8aa3b, v136
	v_mul_f32_e32 v137, 0xbfb8aa3b, v137
	v_rcp_f32_e32 v196, v140
	v_exp_f32_e32 v136, v136
	v_exp_f32_e32 v137, v137
	v_fma_f32 v140, v142, v167, v46
	v_add_f32_e32 v138, 1.0, v138
	v_mul_f32_e32 v140, 0xbfb8aa3b, v140
	v_rcp_f32_e32 v141, v138
	v_fma_f32 v138, v143, v167, v47
	v_fma_f32 v139, v139, v167, v43
	v_exp_f32_e32 v140, v140
	v_mul_f32_e32 v138, 0xbfb8aa3b, v138
	v_mul_f32_e32 v139, 0xbfb8aa3b, v139
	v_exp_f32_e32 v138, v138
	v_exp_f32_e32 v139, v139
	v_add_f32_e32 v136, 1.0, v136
	v_add_f32_e32 v137, 1.0, v137
	v_rcp_f32_e32 v136, v136
	v_rcp_f32_e32 v137, v137
	v_add_f32_e32 v140, 1.0, v140
	v_rcp_f32_e32 v140, v140
	v_add_f32_e32 v138, 1.0, v138
	v_add_f32_e32 v139, 1.0, v139
	v_rcp_f32_e32 v138, v138
	v_rcp_f32_e32 v139, v139
	v_pk_fma_f32 v[136:137], v[136:137], s[36:37], 0.5 op_sel_hi:[1,0,0]
	v_pk_fma_f32 v[142:143], v[196:197], s[36:37], 0.5 op_sel_hi:[1,0,0]
	v_cvt_u32_f32_e32 v188, v136
	v_cvt_u32_f32_e32 v189, v137
	v_cvt_u32_f32_e32 v143, v143
	v_cvt_u32_f32_e32 v142, v142
	v_pk_fma_f32 v[136:137], v[140:141], s[36:37], 0.5 op_sel_hi:[1,0,0]
	v_fma_f32 v128, v128, v167, v24
	v_cvt_u32_f32_sdwa v140, v136 dst_sel:WORD_1 dst_unused:UNUSED_PAD src0_sel:DWORD
	v_cvt_u32_f32_sdwa v141, v137 dst_sel:WORD_1 dst_unused:UNUSED_PAD src0_sel:DWORD
	v_pk_fma_f32 v[136:137], v[138:139], s[36:37], 0.5 op_sel_hi:[1,0,0]
	v_lshlrev_b32_e32 v138, 8, v189
	v_cvt_u32_f32_sdwa v136, v136 dst_sel:BYTE_3 dst_unused:UNUSED_PAD src0_sel:DWORD
	v_cvt_u32_f32_sdwa v137, v137 dst_sel:BYTE_3 dst_unused:UNUSED_PAD src0_sel:DWORD
	v_lshlrev_b32_e32 v139, 8, v188
	v_mul_f32_e32 v128, 0xbfb8aa3b, v128
	v_or_b32_e32 v138, v138, v143
	v_or_b32_e32 v139, v139, v142
	v_fma_f32 v132, v132, v167, v28
	v_exp_f32_e32 v128, v128
	v_or_b32_e32 v138, v138, v141
	v_or_b32_e32 v139, v139, v140
	v_mul_f32_e32 v132, 0xbfb8aa3b, v132
	v_fma_f32 v130, v130, v167, v26
	v_or_b32_e32 v141, v138, v137
	v_or_b32_e32 v140, v139, v136
	v_mov_b64_e32 v[136:137], s[14:15]
	v_exp_f32_e32 v132, v132
	v_mul_f32_e32 v130, 0xbfb8aa3b, v130
	v_mad_i64_i32 v[138:139], s[18:19], v166, s28, v[136:137]
	v_exp_f32_e32 v130, v130
	v_lshl_add_u64 v[138:139], v[138:139], 0, v[164:165]
	v_add_f32_e32 v128, 1.0, v128
	v_mov_b64_e32 v[236:237], v[140:141]
	v_mov_b32_e32 v190, v194
	v_mov_b32_e32 v191, 0
	v_lshl_add_u64 v[138:139], v[138:139], 0, v[190:191]
	v_rcp_f32_e32 v141, v128
	v_fma_f32 v128, v133, v167, v29
	v_fma_f32 v129, v129, v167, v25
	v_add_f32_e32 v132, 1.0, v132
	v_mul_f32_e32 v128, 0xbfb8aa3b, v128
	v_mul_f32_e32 v129, 0xbfb8aa3b, v129
	v_rcp_f32_e32 v140, v132
	v_exp_f32_e32 v128, v128
	v_exp_f32_e32 v129, v129
	v_fma_f32 v132, v134, v167, v30
	v_add_f32_e32 v130, 1.0, v130
	v_mul_f32_e32 v132, 0xbfb8aa3b, v132
	v_rcp_f32_e32 v133, v130
	v_fma_f32 v130, v135, v167, v31
	v_fma_f32 v131, v131, v167, v27
	v_exp_f32_e32 v132, v132
	v_mul_f32_e32 v130, 0xbfb8aa3b, v130
	v_mul_f32_e32 v131, 0xbfb8aa3b, v131
	v_exp_f32_e32 v130, v130
	v_exp_f32_e32 v131, v131
	v_add_f32_e32 v128, 1.0, v128
	v_add_f32_e32 v129, 1.0, v129
	v_rcp_f32_e32 v128, v128
	v_rcp_f32_e32 v129, v129
	v_add_f32_e32 v132, 1.0, v132
	v_rcp_f32_e32 v132, v132
	v_add_f32_e32 v130, 1.0, v130
	v_add_f32_e32 v131, 1.0, v131
	v_rcp_f32_e32 v130, v130
	v_rcp_f32_e32 v131, v131
	v_pk_fma_f32 v[128:129], v[128:129], s[36:37], 0.5 op_sel_hi:[1,0,0]
	v_pk_fma_f32 v[134:135], v[140:141], s[36:37], 0.5 op_sel_hi:[1,0,0]
	v_cvt_u32_f32_e32 v140, v128
	v_cvt_u32_f32_e32 v141, v129
	v_cvt_u32_f32_e32 v135, v135
	v_cvt_u32_f32_e32 v134, v134
	v_pk_fma_f32 v[128:129], v[132:133], s[36:37], 0.5 op_sel_hi:[1,0,0]
	s_nop 0
	v_cvt_u32_f32_sdwa v132, v128 dst_sel:WORD_1 dst_unused:UNUSED_PAD src0_sel:DWORD
	v_cvt_u32_f32_sdwa v133, v129 dst_sel:WORD_1 dst_unused:UNUSED_PAD src0_sel:DWORD
	v_pk_fma_f32 v[128:129], v[130:131], s[36:37], 0.5 op_sel_hi:[1,0,0]
	v_lshlrev_b32_e32 v130, 8, v141
	v_cvt_u32_f32_sdwa v128, v128 dst_sel:BYTE_3 dst_unused:UNUSED_PAD src0_sel:DWORD
	v_cvt_u32_f32_sdwa v129, v129 dst_sel:BYTE_3 dst_unused:UNUSED_PAD src0_sel:DWORD
	v_lshlrev_b32_e32 v131, 8, v140
	v_or_b32_e32 v130, v130, v135
	v_or_b32_e32 v131, v131, v134
	v_or_b32_e32 v130, v130, v133
	v_or_b32_e32 v131, v131, v132
	v_or_b32_e32 v129, v130, v129
	v_or_b32_e32 v128, v131, v128
	v_mov_b64_e32 v[238:239], v[128:129]
	global_store_dwordx4 v[138:139], v[236:239], off
	s_nop 1
	v_or_b32_e32 v128, 16, v166
	v_ashrrev_i32_e32 v129, 31, v128
	v_lshlrev_b64 v[130:131], 6, v[128:129]
	v_lshl_add_u64 v[134:135], s[26:27], 0, v[130:131]
	s_nop 0
	s_nop 0
	s_nop 0
	s_nop 0
	v_mov_b32_e32 v129, v207
	v_fma_f32 v120, v120, v129, v40
	v_mul_f32_e32 v120, 0xbfb8aa3b, v120
	v_fma_f32 v124, v124, v129, v44
	v_exp_f32_e32 v120, v120
	v_mul_f32_e32 v124, 0xbfb8aa3b, v124
	v_fma_f32 v122, v122, v129, v42
	v_exp_f32_e32 v124, v124
	v_mul_f32_e32 v122, 0xbfb8aa3b, v122
	v_exp_f32_e32 v122, v122
	v_add_f32_e32 v120, 1.0, v120
	v_rcp_f32_e32 v131, v120
	v_fma_f32 v120, v125, v129, v45
	v_fma_f32 v121, v121, v129, v41
	v_add_f32_e32 v124, 1.0, v124
	v_mul_f32_e32 v120, 0xbfb8aa3b, v120
	v_mul_f32_e32 v121, 0xbfb8aa3b, v121
	v_rcp_f32_e32 v130, v124
	v_exp_f32_e32 v120, v120
	v_exp_f32_e32 v121, v121
	v_fma_f32 v124, v126, v129, v46
	v_add_f32_e32 v122, 1.0, v122
	v_mul_f32_e32 v124, 0xbfb8aa3b, v124
	v_rcp_f32_e32 v125, v122
	v_fma_f32 v122, v127, v129, v47
	v_fma_f32 v123, v123, v129, v43
	v_exp_f32_e32 v124, v124
	v_mul_f32_e32 v122, 0xbfb8aa3b, v122
	v_mul_f32_e32 v123, 0xbfb8aa3b, v123
	v_exp_f32_e32 v122, v122
	v_exp_f32_e32 v123, v123
	v_add_f32_e32 v120, 1.0, v120
	v_add_f32_e32 v121, 1.0, v121
	v_rcp_f32_e32 v120, v120
	v_rcp_f32_e32 v121, v121
	v_add_f32_e32 v124, 1.0, v124
	v_rcp_f32_e32 v124, v124
	v_add_f32_e32 v122, 1.0, v122
	v_add_f32_e32 v123, 1.0, v123
	v_rcp_f32_e32 v122, v122
	v_rcp_f32_e32 v123, v123
	v_pk_fma_f32 v[120:121], v[120:121], s[36:37], 0.5 op_sel_hi:[1,0,0]
	v_pk_fma_f32 v[126:127], v[130:131], s[36:37], 0.5 op_sel_hi:[1,0,0]
	v_cvt_u32_f32_e32 v130, v120
	v_cvt_u32_f32_e32 v131, v121
	v_cvt_u32_f32_e32 v127, v127
	v_cvt_u32_f32_e32 v126, v126
	v_pk_fma_f32 v[120:121], v[124:125], s[36:37], 0.5 op_sel_hi:[1,0,0]
	v_fma_f32 v112, v112, v129, v24
	v_cvt_u32_f32_sdwa v124, v120 dst_sel:WORD_1 dst_unused:UNUSED_PAD src0_sel:DWORD
	v_cvt_u32_f32_sdwa v125, v121 dst_sel:WORD_1 dst_unused:UNUSED_PAD src0_sel:DWORD
	v_pk_fma_f32 v[120:121], v[122:123], s[36:37], 0.5 op_sel_hi:[1,0,0]
	v_mul_f32_e32 v112, 0xbfb8aa3b, v112
	v_cvt_u32_f32_sdwa v120, v120 dst_sel:BYTE_3 dst_unused:UNUSED_PAD src0_sel:DWORD
	v_cvt_u32_f32_sdwa v121, v121 dst_sel:BYTE_3 dst_unused:UNUSED_PAD src0_sel:DWORD
	v_lshlrev_b32_e32 v122, 8, v131
	v_lshlrev_b32_e32 v123, 8, v130
	v_fma_f32 v116, v116, v129, v28
	v_exp_f32_e32 v112, v112
	v_or_b32_e32 v122, v122, v127
	v_or_b32_e32 v123, v123, v126
	v_mul_f32_e32 v116, 0xbfb8aa3b, v116
	v_fma_f32 v114, v114, v129, v26
	v_or_b32_e32 v122, v122, v125
	v_or_b32_e32 v124, v123, v124
	v_exp_f32_e32 v116, v116
	v_mul_f32_e32 v114, 0xbfb8aa3b, v114
	v_or_b32_e32 v123, v122, v121
	v_or_b32_e32 v122, v124, v120
	v_mad_i64_i32 v[120:121], s[18:19], v128, s28, v[136:137]
	v_exp_f32_e32 v114, v114
	v_lshl_add_u64 v[120:121], v[120:121], 0, v[164:165]
	v_add_f32_e32 v112, 1.0, v112
	v_mov_b64_e32 v[236:237], v[122:123]
	v_mov_b32_e32 v190, v194
	v_mov_b32_e32 v191, 0
	v_lshl_add_u64 v[120:121], v[120:121], 0, v[190:191]
	v_rcp_f32_e32 v123, v112
	v_fma_f32 v112, v117, v129, v29
	v_fma_f32 v113, v113, v129, v25
	v_add_f32_e32 v116, 1.0, v116
	v_mul_f32_e32 v112, 0xbfb8aa3b, v112
	v_mul_f32_e32 v113, 0xbfb8aa3b, v113
	v_rcp_f32_e32 v122, v116
	v_exp_f32_e32 v112, v112
	v_exp_f32_e32 v113, v113
	v_fma_f32 v116, v118, v129, v30
	v_add_f32_e32 v114, 1.0, v114
	v_mul_f32_e32 v116, 0xbfb8aa3b, v116
	v_rcp_f32_e32 v117, v114
	v_fma_f32 v114, v119, v129, v31
	v_fma_f32 v115, v115, v129, v27
	v_exp_f32_e32 v116, v116
	v_mul_f32_e32 v114, 0xbfb8aa3b, v114
	v_mul_f32_e32 v115, 0xbfb8aa3b, v115
	v_exp_f32_e32 v114, v114
	v_exp_f32_e32 v115, v115
	v_add_f32_e32 v112, 1.0, v112
	v_add_f32_e32 v113, 1.0, v113
	v_rcp_f32_e32 v112, v112
	v_rcp_f32_e32 v113, v113
	v_add_f32_e32 v116, 1.0, v116
	v_rcp_f32_e32 v116, v116
	v_add_f32_e32 v114, 1.0, v114
	v_add_f32_e32 v115, 1.0, v115
	v_rcp_f32_e32 v114, v114
	v_rcp_f32_e32 v115, v115
	v_pk_fma_f32 v[112:113], v[112:113], s[36:37], 0.5 op_sel_hi:[1,0,0]
	v_pk_fma_f32 v[118:119], v[122:123], s[36:37], 0.5 op_sel_hi:[1,0,0]
	v_cvt_u32_f32_e32 v122, v112
	v_cvt_u32_f32_e32 v123, v113
	v_cvt_u32_f32_e32 v119, v119
	v_cvt_u32_f32_e32 v118, v118
	v_pk_fma_f32 v[112:113], v[116:117], s[36:37], 0.5 op_sel_hi:[1,0,0]
	s_nop 0
	v_cvt_u32_f32_sdwa v116, v112 dst_sel:WORD_1 dst_unused:UNUSED_PAD src0_sel:DWORD
	v_cvt_u32_f32_sdwa v117, v113 dst_sel:WORD_1 dst_unused:UNUSED_PAD src0_sel:DWORD
	v_pk_fma_f32 v[112:113], v[114:115], s[36:37], 0.5 op_sel_hi:[1,0,0]
	v_lshlrev_b32_e32 v114, 8, v123
	v_cvt_u32_f32_sdwa v112, v112 dst_sel:BYTE_3 dst_unused:UNUSED_PAD src0_sel:DWORD
	v_cvt_u32_f32_sdwa v113, v113 dst_sel:BYTE_3 dst_unused:UNUSED_PAD src0_sel:DWORD
	v_lshlrev_b32_e32 v115, 8, v122
	v_or_b32_e32 v114, v114, v119
	v_or_b32_e32 v115, v115, v118
	v_or_b32_e32 v114, v114, v117
	v_or_b32_e32 v115, v115, v116
	v_or_b32_e32 v113, v114, v113
	v_or_b32_e32 v112, v115, v112
	v_mov_b64_e32 v[238:239], v[112:113]
	global_store_dwordx4 v[120:121], v[236:239], off
	s_nop 1
	v_or_b32_e32 v112, 32, v166
	v_ashrrev_i32_e32 v113, 31, v112
	v_lshlrev_b64 v[114:115], 6, v[112:113]
	v_lshl_add_u64 v[126:127], s[26:27], 0, v[114:115]
	s_nop 0
	s_nop 0
	s_nop 0
	s_nop 0
	s_nop 0
	v_mov_b32_e32 v113, v215
	v_fma_f32 v104, v104, v113, v40
	v_mul_f32_e32 v104, 0xbfb8aa3b, v104
	v_fma_f32 v108, v108, v113, v44
	v_exp_f32_e32 v104, v104
	v_mul_f32_e32 v108, 0xbfb8aa3b, v108
	v_fma_f32 v106, v106, v113, v42
	v_exp_f32_e32 v108, v108
	v_mul_f32_e32 v106, 0xbfb8aa3b, v106
	v_exp_f32_e32 v106, v106
	v_add_f32_e32 v104, 1.0, v104
	v_rcp_f32_e32 v115, v104
	v_fma_f32 v104, v109, v113, v45
	v_fma_f32 v105, v105, v113, v41
	v_add_f32_e32 v108, 1.0, v108
	v_mul_f32_e32 v104, 0xbfb8aa3b, v104
	v_mul_f32_e32 v105, 0xbfb8aa3b, v105
	v_rcp_f32_e32 v114, v108
	v_exp_f32_e32 v104, v104
	v_exp_f32_e32 v105, v105
	v_fma_f32 v108, v110, v113, v46
	v_add_f32_e32 v106, 1.0, v106
	v_mul_f32_e32 v108, 0xbfb8aa3b, v108
	v_rcp_f32_e32 v109, v106
	v_fma_f32 v106, v111, v113, v47
	v_fma_f32 v107, v107, v113, v43
	v_exp_f32_e32 v108, v108
	v_mul_f32_e32 v106, 0xbfb8aa3b, v106
	v_mul_f32_e32 v107, 0xbfb8aa3b, v107
	v_exp_f32_e32 v106, v106
	v_exp_f32_e32 v107, v107
	v_add_f32_e32 v104, 1.0, v104
	v_add_f32_e32 v105, 1.0, v105
	v_rcp_f32_e32 v104, v104
	v_rcp_f32_e32 v105, v105
	v_add_f32_e32 v108, 1.0, v108
	v_rcp_f32_e32 v108, v108
	v_add_f32_e32 v106, 1.0, v106
	v_add_f32_e32 v107, 1.0, v107
	v_rcp_f32_e32 v106, v106
	v_rcp_f32_e32 v107, v107
	v_pk_fma_f32 v[104:105], v[104:105], s[36:37], 0.5 op_sel_hi:[1,0,0]
	v_pk_fma_f32 v[110:111], v[114:115], s[36:37], 0.5 op_sel_hi:[1,0,0]
	v_cvt_u32_f32_e32 v114, v104
	v_cvt_u32_f32_e32 v115, v105
	v_cvt_u32_f32_e32 v111, v111
	v_cvt_u32_f32_e32 v110, v110
	v_pk_fma_f32 v[104:105], v[108:109], s[36:37], 0.5 op_sel_hi:[1,0,0]
	v_fma_f32 v96, v96, v113, v24
	v_cvt_u32_f32_sdwa v108, v104 dst_sel:WORD_1 dst_unused:UNUSED_PAD src0_sel:DWORD
	v_cvt_u32_f32_sdwa v109, v105 dst_sel:WORD_1 dst_unused:UNUSED_PAD src0_sel:DWORD
	v_pk_fma_f32 v[104:105], v[106:107], s[36:37], 0.5 op_sel_hi:[1,0,0]
	v_mul_f32_e32 v96, 0xbfb8aa3b, v96
	v_cvt_u32_f32_sdwa v104, v104 dst_sel:BYTE_3 dst_unused:UNUSED_PAD src0_sel:DWORD
	v_cvt_u32_f32_sdwa v105, v105 dst_sel:BYTE_3 dst_unused:UNUSED_PAD src0_sel:DWORD
	v_lshlrev_b32_e32 v106, 8, v115
	v_lshlrev_b32_e32 v107, 8, v114
	v_fma_f32 v100, v100, v113, v28
	v_exp_f32_e32 v96, v96
	v_or_b32_e32 v106, v106, v111
	v_or_b32_e32 v107, v107, v110
	v_mul_f32_e32 v100, 0xbfb8aa3b, v100
	v_fma_f32 v98, v98, v113, v26
	v_or_b32_e32 v106, v106, v109
	v_or_b32_e32 v108, v107, v108
	v_exp_f32_e32 v100, v100
	v_mul_f32_e32 v98, 0xbfb8aa3b, v98
	v_or_b32_e32 v107, v106, v105
	v_or_b32_e32 v106, v108, v104
	v_mad_i64_i32 v[104:105], s[18:19], v112, s28, v[136:137]
	v_exp_f32_e32 v98, v98
	v_lshl_add_u64 v[104:105], v[104:105], 0, v[164:165]
	v_add_f32_e32 v96, 1.0, v96
	v_mov_b64_e32 v[236:237], v[106:107]
	v_mov_b32_e32 v190, v194
	v_mov_b32_e32 v191, 0
	v_lshl_add_u64 v[104:105], v[104:105], 0, v[190:191]
	v_rcp_f32_e32 v107, v96
	v_fma_f32 v96, v101, v113, v29
	v_fma_f32 v97, v97, v113, v25
	v_add_f32_e32 v100, 1.0, v100
	v_mul_f32_e32 v96, 0xbfb8aa3b, v96
	v_mul_f32_e32 v97, 0xbfb8aa3b, v97
	v_rcp_f32_e32 v106, v100
	v_exp_f32_e32 v96, v96
	v_exp_f32_e32 v97, v97
	v_fma_f32 v100, v102, v113, v30
	v_add_f32_e32 v98, 1.0, v98
	v_mul_f32_e32 v100, 0xbfb8aa3b, v100
	v_rcp_f32_e32 v101, v98
	v_fma_f32 v98, v103, v113, v31
	v_fma_f32 v99, v99, v113, v27
	v_exp_f32_e32 v100, v100
	v_mul_f32_e32 v98, 0xbfb8aa3b, v98
	v_mul_f32_e32 v99, 0xbfb8aa3b, v99
	v_exp_f32_e32 v98, v98
	v_exp_f32_e32 v99, v99
	v_add_f32_e32 v96, 1.0, v96
	v_add_f32_e32 v97, 1.0, v97
	v_rcp_f32_e32 v96, v96
	v_rcp_f32_e32 v97, v97
	v_add_f32_e32 v100, 1.0, v100
	v_rcp_f32_e32 v100, v100
	v_add_f32_e32 v98, 1.0, v98
	v_add_f32_e32 v99, 1.0, v99
	v_rcp_f32_e32 v98, v98
	v_rcp_f32_e32 v99, v99
	v_pk_fma_f32 v[96:97], v[96:97], s[36:37], 0.5 op_sel_hi:[1,0,0]
	v_pk_fma_f32 v[102:103], v[106:107], s[36:37], 0.5 op_sel_hi:[1,0,0]
	v_cvt_u32_f32_e32 v106, v96
	v_cvt_u32_f32_e32 v107, v97
	v_cvt_u32_f32_e32 v103, v103
	v_cvt_u32_f32_e32 v102, v102
	v_pk_fma_f32 v[96:97], v[100:101], s[36:37], 0.5 op_sel_hi:[1,0,0]
	s_nop 0
	v_cvt_u32_f32_sdwa v100, v96 dst_sel:WORD_1 dst_unused:UNUSED_PAD src0_sel:DWORD
	v_cvt_u32_f32_sdwa v101, v97 dst_sel:WORD_1 dst_unused:UNUSED_PAD src0_sel:DWORD
	v_pk_fma_f32 v[96:97], v[98:99], s[36:37], 0.5 op_sel_hi:[1,0,0]
	v_lshlrev_b32_e32 v98, 8, v107
	v_cvt_u32_f32_sdwa v96, v96 dst_sel:BYTE_3 dst_unused:UNUSED_PAD src0_sel:DWORD
	v_cvt_u32_f32_sdwa v97, v97 dst_sel:BYTE_3 dst_unused:UNUSED_PAD src0_sel:DWORD
	v_lshlrev_b32_e32 v99, 8, v106
	v_or_b32_e32 v98, v98, v103
	v_or_b32_e32 v99, v99, v102
	v_or_b32_e32 v98, v98, v101
	v_or_b32_e32 v99, v99, v100
	v_or_b32_e32 v97, v98, v97
	v_or_b32_e32 v96, v99, v96
	v_mov_b64_e32 v[238:239], v[96:97]
	global_store_dwordx4 v[104:105], v[236:239], off
	s_nop 1
	v_or_b32_e32 v96, 48, v166
	v_ashrrev_i32_e32 v97, 31, v96
	v_lshlrev_b64 v[98:99], 6, v[96:97]
	v_lshl_add_u64 v[110:111], s[26:27], 0, v[98:99]
	s_nop 0
	s_nop 0
	s_nop 0
	s_nop 0
	s_nop 0
	v_mov_b32_e32 v97, v219
	v_fma_f32 v88, v88, v97, v40
	v_mul_f32_e32 v88, 0xbfb8aa3b, v88
	v_fma_f32 v92, v92, v97, v44
	v_exp_f32_e32 v88, v88
	v_mul_f32_e32 v92, 0xbfb8aa3b, v92
	v_fma_f32 v90, v90, v97, v42
	v_exp_f32_e32 v92, v92
	v_mul_f32_e32 v90, 0xbfb8aa3b, v90
	v_exp_f32_e32 v90, v90
	v_add_f32_e32 v88, 1.0, v88
	v_rcp_f32_e32 v99, v88
	v_fma_f32 v88, v93, v97, v45
	v_fma_f32 v89, v89, v97, v41
	v_add_f32_e32 v92, 1.0, v92
	v_mul_f32_e32 v88, 0xbfb8aa3b, v88
	v_mul_f32_e32 v89, 0xbfb8aa3b, v89
	v_rcp_f32_e32 v98, v92
	v_exp_f32_e32 v88, v88
	v_exp_f32_e32 v89, v89
	v_fma_f32 v92, v94, v97, v46
	v_add_f32_e32 v90, 1.0, v90
	v_mul_f32_e32 v92, 0xbfb8aa3b, v92
	v_rcp_f32_e32 v93, v90
	v_fma_f32 v90, v95, v97, v47
	v_fma_f32 v91, v91, v97, v43
	v_exp_f32_e32 v92, v92
	v_mul_f32_e32 v90, 0xbfb8aa3b, v90
	v_mul_f32_e32 v91, 0xbfb8aa3b, v91
	v_exp_f32_e32 v90, v90
	v_exp_f32_e32 v91, v91
	v_add_f32_e32 v88, 1.0, v88
	v_add_f32_e32 v89, 1.0, v89
	v_rcp_f32_e32 v88, v88
	v_rcp_f32_e32 v89, v89
	v_add_f32_e32 v92, 1.0, v92
	v_rcp_f32_e32 v92, v92
	v_add_f32_e32 v90, 1.0, v90
	v_add_f32_e32 v91, 1.0, v91
	v_rcp_f32_e32 v90, v90
	v_rcp_f32_e32 v91, v91
	v_pk_fma_f32 v[88:89], v[88:89], s[36:37], 0.5 op_sel_hi:[1,0,0]
	v_pk_fma_f32 v[94:95], v[98:99], s[36:37], 0.5 op_sel_hi:[1,0,0]
	v_cvt_u32_f32_e32 v98, v88
	v_cvt_u32_f32_e32 v99, v89
	v_cvt_u32_f32_e32 v95, v95
	v_cvt_u32_f32_e32 v94, v94
	v_pk_fma_f32 v[88:89], v[92:93], s[36:37], 0.5 op_sel_hi:[1,0,0]
	v_fma_f32 v80, v80, v97, v24
	v_cvt_u32_f32_sdwa v92, v88 dst_sel:WORD_1 dst_unused:UNUSED_PAD src0_sel:DWORD
	v_cvt_u32_f32_sdwa v93, v89 dst_sel:WORD_1 dst_unused:UNUSED_PAD src0_sel:DWORD
	v_pk_fma_f32 v[88:89], v[90:91], s[36:37], 0.5 op_sel_hi:[1,0,0]
	v_mul_f32_e32 v80, 0xbfb8aa3b, v80
	v_cvt_u32_f32_sdwa v88, v88 dst_sel:BYTE_3 dst_unused:UNUSED_PAD src0_sel:DWORD
	v_cvt_u32_f32_sdwa v89, v89 dst_sel:BYTE_3 dst_unused:UNUSED_PAD src0_sel:DWORD
	v_lshlrev_b32_e32 v90, 8, v99
	v_lshlrev_b32_e32 v91, 8, v98
	v_fma_f32 v84, v84, v97, v28
	v_exp_f32_e32 v80, v80
	v_or_b32_e32 v90, v90, v95
	v_or_b32_e32 v91, v91, v94
	v_mul_f32_e32 v84, 0xbfb8aa3b, v84
	v_fma_f32 v82, v82, v97, v26
	v_or_b32_e32 v90, v90, v93
	v_or_b32_e32 v92, v91, v92
	v_exp_f32_e32 v84, v84
	v_mul_f32_e32 v82, 0xbfb8aa3b, v82
	v_or_b32_e32 v91, v90, v89
	v_or_b32_e32 v90, v92, v88
	v_mad_i64_i32 v[88:89], s[18:19], v96, s28, v[136:137]
	v_exp_f32_e32 v82, v82
	v_lshl_add_u64 v[88:89], v[88:89], 0, v[164:165]
	v_add_f32_e32 v80, 1.0, v80
	v_mov_b64_e32 v[236:237], v[90:91]
	v_mov_b32_e32 v190, v194
	v_mov_b32_e32 v191, 0
	v_lshl_add_u64 v[88:89], v[88:89], 0, v[190:191]
	v_rcp_f32_e32 v91, v80
	v_fma_f32 v80, v85, v97, v29
	v_fma_f32 v81, v81, v97, v25
	v_add_f32_e32 v84, 1.0, v84
	v_mul_f32_e32 v80, 0xbfb8aa3b, v80
	v_mul_f32_e32 v81, 0xbfb8aa3b, v81
	v_rcp_f32_e32 v90, v84
	v_exp_f32_e32 v80, v80
	v_exp_f32_e32 v81, v81
	v_fma_f32 v84, v86, v97, v30
	v_add_f32_e32 v82, 1.0, v82
	v_mul_f32_e32 v84, 0xbfb8aa3b, v84
	v_rcp_f32_e32 v85, v82
	v_fma_f32 v82, v87, v97, v31
	v_fma_f32 v83, v83, v97, v27
	v_exp_f32_e32 v84, v84
	v_mul_f32_e32 v82, 0xbfb8aa3b, v82
	v_mul_f32_e32 v83, 0xbfb8aa3b, v83
	v_exp_f32_e32 v82, v82
	v_exp_f32_e32 v83, v83
	v_add_f32_e32 v80, 1.0, v80
	v_add_f32_e32 v81, 1.0, v81
	v_rcp_f32_e32 v80, v80
	v_rcp_f32_e32 v81, v81
	v_add_f32_e32 v84, 1.0, v84
	v_rcp_f32_e32 v84, v84
	v_add_f32_e32 v82, 1.0, v82
	v_add_f32_e32 v83, 1.0, v83
	v_rcp_f32_e32 v82, v82
	v_rcp_f32_e32 v83, v83
	v_pk_fma_f32 v[80:81], v[80:81], s[36:37], 0.5 op_sel_hi:[1,0,0]
	v_pk_fma_f32 v[86:87], v[90:91], s[36:37], 0.5 op_sel_hi:[1,0,0]
	v_cvt_u32_f32_e32 v90, v80
	v_cvt_u32_f32_e32 v91, v81
	v_cvt_u32_f32_e32 v87, v87
	v_cvt_u32_f32_e32 v86, v86
	v_pk_fma_f32 v[80:81], v[84:85], s[36:37], 0.5 op_sel_hi:[1,0,0]
	s_nop 0
	v_cvt_u32_f32_sdwa v84, v80 dst_sel:WORD_1 dst_unused:UNUSED_PAD src0_sel:DWORD
	v_cvt_u32_f32_sdwa v85, v81 dst_sel:WORD_1 dst_unused:UNUSED_PAD src0_sel:DWORD
	v_pk_fma_f32 v[80:81], v[82:83], s[36:37], 0.5 op_sel_hi:[1,0,0]
	v_lshlrev_b32_e32 v82, 8, v91
	v_cvt_u32_f32_sdwa v80, v80 dst_sel:BYTE_3 dst_unused:UNUSED_PAD src0_sel:DWORD
	v_cvt_u32_f32_sdwa v81, v81 dst_sel:BYTE_3 dst_unused:UNUSED_PAD src0_sel:DWORD
	v_lshlrev_b32_e32 v83, 8, v90
	v_or_b32_e32 v82, v82, v87
	v_or_b32_e32 v83, v83, v86
	v_or_b32_e32 v82, v82, v85
	v_or_b32_e32 v83, v83, v84
	v_or_b32_e32 v81, v82, v81
	v_or_b32_e32 v80, v83, v80
	v_mov_b64_e32 v[238:239], v[80:81]
	global_store_dwordx4 v[88:89], v[236:239], off
	s_nop 1
	v_add_u32_e32 v80, 0x80, v166
	v_ashrrev_i32_e32 v81, 31, v80
	v_lshlrev_b64 v[82:83], 6, v[80:81]
	v_lshl_add_u64 v[94:95], s[26:27], 0, v[82:83]
	s_nop 0
	s_nop 0
	s_nop 0
	s_nop 0
	s_nop 0
	v_mov_b32_e32 v81, v223
	v_fma_f32 v72, v72, v81, v40
	v_mul_f32_e32 v72, 0xbfb8aa3b, v72
	v_fma_f32 v76, v76, v81, v44
	v_exp_f32_e32 v72, v72
	v_mul_f32_e32 v76, 0xbfb8aa3b, v76
	v_fma_f32 v74, v74, v81, v42
	v_exp_f32_e32 v76, v76
	v_mul_f32_e32 v74, 0xbfb8aa3b, v74
	v_exp_f32_e32 v74, v74
	v_add_f32_e32 v72, 1.0, v72
	v_rcp_f32_e32 v83, v72
	v_fma_f32 v72, v77, v81, v45
	v_fma_f32 v73, v73, v81, v41
	v_add_f32_e32 v76, 1.0, v76
	v_mul_f32_e32 v72, 0xbfb8aa3b, v72
	v_mul_f32_e32 v73, 0xbfb8aa3b, v73
	v_rcp_f32_e32 v82, v76
	v_exp_f32_e32 v72, v72
	v_exp_f32_e32 v73, v73
	v_fma_f32 v76, v78, v81, v46
	v_add_f32_e32 v74, 1.0, v74
	v_mul_f32_e32 v76, 0xbfb8aa3b, v76
	v_rcp_f32_e32 v77, v74
	v_fma_f32 v74, v79, v81, v47
	v_fma_f32 v75, v75, v81, v43
	v_exp_f32_e32 v76, v76
	v_mul_f32_e32 v74, 0xbfb8aa3b, v74
	v_mul_f32_e32 v75, 0xbfb8aa3b, v75
	v_exp_f32_e32 v74, v74
	v_exp_f32_e32 v75, v75
	v_add_f32_e32 v72, 1.0, v72
	v_add_f32_e32 v73, 1.0, v73
	v_rcp_f32_e32 v72, v72
	v_rcp_f32_e32 v73, v73
	v_add_f32_e32 v76, 1.0, v76
	v_rcp_f32_e32 v76, v76
	v_add_f32_e32 v74, 1.0, v74
	v_add_f32_e32 v75, 1.0, v75
	v_rcp_f32_e32 v74, v74
	v_rcp_f32_e32 v75, v75
	v_pk_fma_f32 v[72:73], v[72:73], s[36:37], 0.5 op_sel_hi:[1,0,0]
	v_pk_fma_f32 v[78:79], v[82:83], s[36:37], 0.5 op_sel_hi:[1,0,0]
	v_cvt_u32_f32_e32 v82, v72
	v_cvt_u32_f32_e32 v83, v73
	v_cvt_u32_f32_e32 v79, v79
	v_cvt_u32_f32_e32 v78, v78
	v_pk_fma_f32 v[72:73], v[76:77], s[36:37], 0.5 op_sel_hi:[1,0,0]
	v_fma_f32 v64, v64, v81, v24
	v_cvt_u32_f32_sdwa v76, v72 dst_sel:WORD_1 dst_unused:UNUSED_PAD src0_sel:DWORD
	v_cvt_u32_f32_sdwa v77, v73 dst_sel:WORD_1 dst_unused:UNUSED_PAD src0_sel:DWORD
	v_pk_fma_f32 v[72:73], v[74:75], s[36:37], 0.5 op_sel_hi:[1,0,0]
	v_mul_f32_e32 v64, 0xbfb8aa3b, v64
	v_cvt_u32_f32_sdwa v72, v72 dst_sel:BYTE_3 dst_unused:UNUSED_PAD src0_sel:DWORD
	v_cvt_u32_f32_sdwa v73, v73 dst_sel:BYTE_3 dst_unused:UNUSED_PAD src0_sel:DWORD
	v_lshlrev_b32_e32 v74, 8, v83
	v_lshlrev_b32_e32 v75, 8, v82
	v_fma_f32 v68, v68, v81, v28
	v_exp_f32_e32 v64, v64
	v_or_b32_e32 v74, v74, v79
	v_or_b32_e32 v75, v75, v78
	v_mul_f32_e32 v68, 0xbfb8aa3b, v68
	v_fma_f32 v66, v66, v81, v26
	v_or_b32_e32 v74, v74, v77
	v_or_b32_e32 v76, v75, v76
	v_exp_f32_e32 v68, v68
	v_mul_f32_e32 v66, 0xbfb8aa3b, v66
	v_or_b32_e32 v75, v74, v73
	v_or_b32_e32 v74, v76, v72
	v_mad_i64_i32 v[72:73], s[18:19], v80, s28, v[136:137]
	v_exp_f32_e32 v66, v66
	v_lshl_add_u64 v[72:73], v[72:73], 0, v[164:165]
	v_add_f32_e32 v64, 1.0, v64
	v_mov_b64_e32 v[236:237], v[74:75]
	v_mov_b32_e32 v190, v194
	v_mov_b32_e32 v191, 0
	v_lshl_add_u64 v[72:73], v[72:73], 0, v[190:191]
	v_rcp_f32_e32 v75, v64
	v_fma_f32 v64, v69, v81, v29
	v_fma_f32 v65, v65, v81, v25
	v_add_f32_e32 v68, 1.0, v68
	v_mul_f32_e32 v64, 0xbfb8aa3b, v64
	v_mul_f32_e32 v65, 0xbfb8aa3b, v65
	v_rcp_f32_e32 v74, v68
	v_exp_f32_e32 v64, v64
	v_exp_f32_e32 v65, v65
	v_fma_f32 v68, v70, v81, v30
	v_add_f32_e32 v66, 1.0, v66
	v_mul_f32_e32 v68, 0xbfb8aa3b, v68
	v_rcp_f32_e32 v69, v66
	v_fma_f32 v66, v71, v81, v31
	v_fma_f32 v67, v67, v81, v27
	v_exp_f32_e32 v68, v68
	v_mul_f32_e32 v66, 0xbfb8aa3b, v66
	v_mul_f32_e32 v67, 0xbfb8aa3b, v67
	v_exp_f32_e32 v66, v66
	v_exp_f32_e32 v67, v67
	v_add_f32_e32 v64, 1.0, v64
	v_add_f32_e32 v65, 1.0, v65
	v_rcp_f32_e32 v64, v64
	v_rcp_f32_e32 v65, v65
	v_add_f32_e32 v68, 1.0, v68
	v_rcp_f32_e32 v68, v68
	v_add_f32_e32 v66, 1.0, v66
	v_add_f32_e32 v67, 1.0, v67
	v_rcp_f32_e32 v66, v66
	v_rcp_f32_e32 v67, v67
	v_pk_fma_f32 v[64:65], v[64:65], s[36:37], 0.5 op_sel_hi:[1,0,0]
	v_pk_fma_f32 v[70:71], v[74:75], s[36:37], 0.5 op_sel_hi:[1,0,0]
	v_cvt_u32_f32_e32 v74, v64
	v_cvt_u32_f32_e32 v75, v65
	v_cvt_u32_f32_e32 v71, v71
	v_cvt_u32_f32_e32 v70, v70
	v_pk_fma_f32 v[64:65], v[68:69], s[36:37], 0.5 op_sel_hi:[1,0,0]
	s_nop 0
	v_cvt_u32_f32_sdwa v68, v64 dst_sel:WORD_1 dst_unused:UNUSED_PAD src0_sel:DWORD
	v_cvt_u32_f32_sdwa v69, v65 dst_sel:WORD_1 dst_unused:UNUSED_PAD src0_sel:DWORD
	v_pk_fma_f32 v[64:65], v[66:67], s[36:37], 0.5 op_sel_hi:[1,0,0]
	v_lshlrev_b32_e32 v66, 8, v75
	v_cvt_u32_f32_sdwa v64, v64 dst_sel:BYTE_3 dst_unused:UNUSED_PAD src0_sel:DWORD
	v_cvt_u32_f32_sdwa v65, v65 dst_sel:BYTE_3 dst_unused:UNUSED_PAD src0_sel:DWORD
	v_lshlrev_b32_e32 v67, 8, v74
	v_or_b32_e32 v66, v66, v71
	v_or_b32_e32 v67, v67, v70
	v_or_b32_e32 v66, v66, v69
	v_or_b32_e32 v67, v67, v68
	v_or_b32_e32 v65, v66, v65
	v_or_b32_e32 v64, v67, v64
	v_mov_b64_e32 v[238:239], v[64:65]
	global_store_dwordx4 v[72:73], v[236:239], off
	s_nop 1
	v_add_u32_e32 v64, 0x90, v166
	v_ashrrev_i32_e32 v65, 31, v64
	v_lshlrev_b64 v[66:67], 6, v[64:65]
	v_lshl_add_u64 v[78:79], s[26:27], 0, v[66:67]
	s_nop 0
	s_nop 0
	s_nop 0
	s_nop 0
	s_nop 0
	v_mov_b32_e32 v65, v227
	v_fma_f32 v56, v56, v65, v40
	v_mul_f32_e32 v56, 0xbfb8aa3b, v56
	v_fma_f32 v60, v60, v65, v44
	v_exp_f32_e32 v56, v56
	v_mul_f32_e32 v60, 0xbfb8aa3b, v60
	v_fma_f32 v58, v58, v65, v42
	v_exp_f32_e32 v60, v60
	v_mul_f32_e32 v58, 0xbfb8aa3b, v58
	v_exp_f32_e32 v58, v58
	v_add_f32_e32 v56, 1.0, v56
	v_rcp_f32_e32 v67, v56
	v_fma_f32 v56, v61, v65, v45
	v_fma_f32 v57, v57, v65, v41
	v_add_f32_e32 v60, 1.0, v60
	v_mul_f32_e32 v56, 0xbfb8aa3b, v56
	v_mul_f32_e32 v57, 0xbfb8aa3b, v57
	v_rcp_f32_e32 v66, v60
	v_exp_f32_e32 v56, v56
	v_exp_f32_e32 v57, v57
	v_fma_f32 v60, v62, v65, v46
	v_add_f32_e32 v58, 1.0, v58
	v_mul_f32_e32 v60, 0xbfb8aa3b, v60
	v_rcp_f32_e32 v61, v58
	v_fma_f32 v58, v63, v65, v47
	v_fma_f32 v59, v59, v65, v43
	v_exp_f32_e32 v60, v60
	v_mul_f32_e32 v58, 0xbfb8aa3b, v58
	v_mul_f32_e32 v59, 0xbfb8aa3b, v59
	v_exp_f32_e32 v58, v58
	v_exp_f32_e32 v59, v59
	v_add_f32_e32 v56, 1.0, v56
	v_add_f32_e32 v57, 1.0, v57
	v_rcp_f32_e32 v56, v56
	v_rcp_f32_e32 v57, v57
	v_add_f32_e32 v60, 1.0, v60
	v_rcp_f32_e32 v60, v60
	v_add_f32_e32 v58, 1.0, v58
	v_add_f32_e32 v59, 1.0, v59
	v_rcp_f32_e32 v58, v58
	v_rcp_f32_e32 v59, v59
	v_pk_fma_f32 v[56:57], v[56:57], s[36:37], 0.5 op_sel_hi:[1,0,0]
	v_pk_fma_f32 v[62:63], v[66:67], s[36:37], 0.5 op_sel_hi:[1,0,0]
	v_cvt_u32_f32_e32 v66, v56
	v_cvt_u32_f32_e32 v67, v57
	v_cvt_u32_f32_e32 v63, v63
	v_cvt_u32_f32_e32 v62, v62
	v_pk_fma_f32 v[56:57], v[60:61], s[36:37], 0.5 op_sel_hi:[1,0,0]
	v_fma_f32 v48, v48, v65, v24
	v_cvt_u32_f32_sdwa v60, v56 dst_sel:WORD_1 dst_unused:UNUSED_PAD src0_sel:DWORD
	v_cvt_u32_f32_sdwa v61, v57 dst_sel:WORD_1 dst_unused:UNUSED_PAD src0_sel:DWORD
	v_pk_fma_f32 v[56:57], v[58:59], s[36:37], 0.5 op_sel_hi:[1,0,0]
	v_mul_f32_e32 v48, 0xbfb8aa3b, v48
	v_cvt_u32_f32_sdwa v56, v56 dst_sel:BYTE_3 dst_unused:UNUSED_PAD src0_sel:DWORD
	v_cvt_u32_f32_sdwa v57, v57 dst_sel:BYTE_3 dst_unused:UNUSED_PAD src0_sel:DWORD
	v_lshlrev_b32_e32 v58, 8, v67
	v_lshlrev_b32_e32 v59, 8, v66
	v_fma_f32 v52, v52, v65, v28
	v_exp_f32_e32 v48, v48
	v_or_b32_e32 v58, v58, v63
	v_or_b32_e32 v59, v59, v62
	v_mul_f32_e32 v52, 0xbfb8aa3b, v52
	v_fma_f32 v50, v50, v65, v26
	v_or_b32_e32 v58, v58, v61
	v_or_b32_e32 v60, v59, v60
	v_exp_f32_e32 v52, v52
	v_mul_f32_e32 v50, 0xbfb8aa3b, v50
	v_or_b32_e32 v59, v58, v57
	v_or_b32_e32 v58, v60, v56
	v_mad_i64_i32 v[56:57], s[18:19], v64, s28, v[136:137]
	v_exp_f32_e32 v50, v50
	v_lshl_add_u64 v[56:57], v[56:57], 0, v[164:165]
	v_add_f32_e32 v48, 1.0, v48
	v_mov_b64_e32 v[236:237], v[58:59]
	v_mov_b32_e32 v190, v194
	v_mov_b32_e32 v191, 0
	v_lshl_add_u64 v[56:57], v[56:57], 0, v[190:191]
	v_rcp_f32_e32 v59, v48
	v_fma_f32 v48, v53, v65, v29
	v_fma_f32 v49, v49, v65, v25
	v_add_f32_e32 v52, 1.0, v52
	v_mul_f32_e32 v48, 0xbfb8aa3b, v48
	v_mul_f32_e32 v49, 0xbfb8aa3b, v49
	v_rcp_f32_e32 v58, v52
	v_exp_f32_e32 v48, v48
	v_exp_f32_e32 v49, v49
	v_fma_f32 v52, v54, v65, v30
	v_add_f32_e32 v50, 1.0, v50
	v_mul_f32_e32 v52, 0xbfb8aa3b, v52
	v_rcp_f32_e32 v53, v50
	v_fma_f32 v50, v55, v65, v31
	v_fma_f32 v51, v51, v65, v27
	v_exp_f32_e32 v52, v52
	v_mul_f32_e32 v50, 0xbfb8aa3b, v50
	v_mul_f32_e32 v51, 0xbfb8aa3b, v51
	v_exp_f32_e32 v50, v50
	v_exp_f32_e32 v51, v51
	v_add_f32_e32 v48, 1.0, v48
	v_add_f32_e32 v49, 1.0, v49
	v_rcp_f32_e32 v48, v48
	v_rcp_f32_e32 v49, v49
	v_add_f32_e32 v52, 1.0, v52
	v_rcp_f32_e32 v52, v52
	v_add_f32_e32 v50, 1.0, v50
	v_add_f32_e32 v51, 1.0, v51
	v_rcp_f32_e32 v50, v50
	v_rcp_f32_e32 v51, v51
	v_pk_fma_f32 v[48:49], v[48:49], s[36:37], 0.5 op_sel_hi:[1,0,0]
	v_pk_fma_f32 v[54:55], v[58:59], s[36:37], 0.5 op_sel_hi:[1,0,0]
	v_cvt_u32_f32_e32 v58, v48
	v_cvt_u32_f32_e32 v59, v49
	v_cvt_u32_f32_e32 v55, v55
	v_cvt_u32_f32_e32 v54, v54
	v_pk_fma_f32 v[48:49], v[52:53], s[36:37], 0.5 op_sel_hi:[1,0,0]
	s_nop 0
	v_cvt_u32_f32_sdwa v52, v48 dst_sel:WORD_1 dst_unused:UNUSED_PAD src0_sel:DWORD
	v_cvt_u32_f32_sdwa v53, v49 dst_sel:WORD_1 dst_unused:UNUSED_PAD src0_sel:DWORD
	v_pk_fma_f32 v[48:49], v[50:51], s[36:37], 0.5 op_sel_hi:[1,0,0]
	v_lshlrev_b32_e32 v50, 8, v59
	v_cvt_u32_f32_sdwa v48, v48 dst_sel:BYTE_3 dst_unused:UNUSED_PAD src0_sel:DWORD
	v_cvt_u32_f32_sdwa v49, v49 dst_sel:BYTE_3 dst_unused:UNUSED_PAD src0_sel:DWORD
	v_lshlrev_b32_e32 v51, 8, v58
	v_or_b32_e32 v50, v50, v55
	v_or_b32_e32 v51, v51, v54
	v_or_b32_e32 v50, v50, v53
	v_or_b32_e32 v51, v51, v52
	v_or_b32_e32 v49, v50, v49
	v_or_b32_e32 v48, v51, v48
	v_mov_b64_e32 v[238:239], v[48:49]
	global_store_dwordx4 v[56:57], v[236:239], off
	s_nop 1
	v_add_u32_e32 v48, 0xa0, v166
	v_ashrrev_i32_e32 v49, 31, v48
	v_lshlrev_b64 v[50:51], 6, v[48:49]
	v_lshl_add_u64 v[62:63], s[26:27], 0, v[50:51]
	s_nop 0
	s_nop 0
	s_nop 0
	s_nop 0
	s_nop 0
	v_mov_b32_e32 v49, v231
	v_fma_f32 v32, v32, v49, v40
	v_mul_f32_e32 v32, 0xbfb8aa3b, v32
	v_fma_f32 v36, v36, v49, v44
	v_exp_f32_e32 v32, v32
	v_mul_f32_e32 v36, 0xbfb8aa3b, v36
	v_fma_f32 v34, v34, v49, v42
	v_exp_f32_e32 v36, v36
	v_mul_f32_e32 v34, 0xbfb8aa3b, v34
	v_exp_f32_e32 v34, v34
	v_add_f32_e32 v32, 1.0, v32
	v_rcp_f32_e32 v51, v32
	v_fma_f32 v32, v37, v49, v45
	v_fma_f32 v33, v33, v49, v41
	v_add_f32_e32 v36, 1.0, v36
	v_mul_f32_e32 v32, 0xbfb8aa3b, v32
	v_mul_f32_e32 v33, 0xbfb8aa3b, v33
	v_rcp_f32_e32 v50, v36
	v_exp_f32_e32 v32, v32
	v_exp_f32_e32 v33, v33
	v_fma_f32 v36, v38, v49, v46
	v_add_f32_e32 v34, 1.0, v34
	v_mul_f32_e32 v36, 0xbfb8aa3b, v36
	v_rcp_f32_e32 v37, v34
	v_fma_f32 v34, v39, v49, v47
	v_fma_f32 v35, v35, v49, v43
	v_exp_f32_e32 v36, v36
	v_mul_f32_e32 v34, 0xbfb8aa3b, v34
	v_mul_f32_e32 v35, 0xbfb8aa3b, v35
	v_exp_f32_e32 v34, v34
	v_exp_f32_e32 v35, v35
	v_add_f32_e32 v32, 1.0, v32
	v_add_f32_e32 v33, 1.0, v33
	v_rcp_f32_e32 v32, v32
	v_rcp_f32_e32 v33, v33
	v_add_f32_e32 v36, 1.0, v36
	v_rcp_f32_e32 v36, v36
	v_add_f32_e32 v34, 1.0, v34
	v_add_f32_e32 v35, 1.0, v35
	v_rcp_f32_e32 v34, v34
	v_rcp_f32_e32 v35, v35
	v_pk_fma_f32 v[32:33], v[32:33], s[36:37], 0.5 op_sel_hi:[1,0,0]
	v_pk_fma_f32 v[38:39], v[50:51], s[36:37], 0.5 op_sel_hi:[1,0,0]
	v_cvt_u32_f32_e32 v50, v32
	v_cvt_u32_f32_e32 v51, v33
	v_cvt_u32_f32_e32 v39, v39
	v_cvt_u32_f32_e32 v38, v38
	v_pk_fma_f32 v[32:33], v[36:37], s[36:37], 0.5 op_sel_hi:[1,0,0]
	v_fma_f32 v16, v16, v49, v24
	v_cvt_u32_f32_sdwa v36, v32 dst_sel:WORD_1 dst_unused:UNUSED_PAD src0_sel:DWORD
	v_cvt_u32_f32_sdwa v37, v33 dst_sel:WORD_1 dst_unused:UNUSED_PAD src0_sel:DWORD
	v_pk_fma_f32 v[32:33], v[34:35], s[36:37], 0.5 op_sel_hi:[1,0,0]
	v_mul_f32_e32 v16, 0xbfb8aa3b, v16
	v_cvt_u32_f32_sdwa v32, v32 dst_sel:BYTE_3 dst_unused:UNUSED_PAD src0_sel:DWORD
	v_cvt_u32_f32_sdwa v33, v33 dst_sel:BYTE_3 dst_unused:UNUSED_PAD src0_sel:DWORD
	v_lshlrev_b32_e32 v34, 8, v51
	v_lshlrev_b32_e32 v35, 8, v50
	v_fma_f32 v20, v20, v49, v28
	v_exp_f32_e32 v16, v16
	v_or_b32_e32 v34, v34, v39
	v_or_b32_e32 v35, v35, v38
	v_mul_f32_e32 v20, 0xbfb8aa3b, v20
	v_fma_f32 v18, v18, v49, v26
	v_or_b32_e32 v34, v34, v37
	v_or_b32_e32 v36, v35, v36
	v_exp_f32_e32 v20, v20
	v_mul_f32_e32 v18, 0xbfb8aa3b, v18
	v_or_b32_e32 v35, v34, v33
	v_or_b32_e32 v34, v36, v32
	v_mad_i64_i32 v[32:33], s[18:19], v48, s28, v[136:137]
	v_exp_f32_e32 v18, v18
	v_lshl_add_u64 v[32:33], v[32:33], 0, v[164:165]
	v_add_f32_e32 v16, 1.0, v16
	v_mov_b64_e32 v[236:237], v[34:35]
	v_mov_b32_e32 v190, v194
	v_mov_b32_e32 v191, 0
	v_lshl_add_u64 v[32:33], v[32:33], 0, v[190:191]
	v_rcp_f32_e32 v35, v16
	v_fma_f32 v16, v21, v49, v29
	v_fma_f32 v17, v17, v49, v25
	v_add_f32_e32 v20, 1.0, v20
	v_mul_f32_e32 v16, 0xbfb8aa3b, v16
	v_mul_f32_e32 v17, 0xbfb8aa3b, v17
	v_rcp_f32_e32 v34, v20
	v_exp_f32_e32 v16, v16
	v_exp_f32_e32 v17, v17
	v_fma_f32 v20, v22, v49, v30
	v_add_f32_e32 v18, 1.0, v18
	v_mul_f32_e32 v20, 0xbfb8aa3b, v20
	v_rcp_f32_e32 v21, v18
	v_fma_f32 v18, v23, v49, v31
	v_fma_f32 v19, v19, v49, v27
	v_exp_f32_e32 v20, v20
	v_mul_f32_e32 v18, 0xbfb8aa3b, v18
	v_mul_f32_e32 v19, 0xbfb8aa3b, v19
	v_exp_f32_e32 v18, v18
	v_exp_f32_e32 v19, v19
	v_add_f32_e32 v16, 1.0, v16
	v_add_f32_e32 v17, 1.0, v17
	v_rcp_f32_e32 v16, v16
	v_rcp_f32_e32 v17, v17
	v_add_f32_e32 v20, 1.0, v20
	v_rcp_f32_e32 v20, v20
	v_add_f32_e32 v18, 1.0, v18
	v_add_f32_e32 v19, 1.0, v19
	v_rcp_f32_e32 v18, v18
	v_rcp_f32_e32 v19, v19
	v_pk_fma_f32 v[16:17], v[16:17], s[36:37], 0.5 op_sel_hi:[1,0,0]
	v_pk_fma_f32 v[22:23], v[34:35], s[36:37], 0.5 op_sel_hi:[1,0,0]
	v_cvt_u32_f32_e32 v34, v16
	v_cvt_u32_f32_e32 v35, v17
	v_cvt_u32_f32_e32 v23, v23
	v_cvt_u32_f32_e32 v22, v22
	v_pk_fma_f32 v[16:17], v[20:21], s[36:37], 0.5 op_sel_hi:[1,0,0]
	s_nop 0
	v_cvt_u32_f32_sdwa v20, v16 dst_sel:WORD_1 dst_unused:UNUSED_PAD src0_sel:DWORD
	v_cvt_u32_f32_sdwa v21, v17 dst_sel:WORD_1 dst_unused:UNUSED_PAD src0_sel:DWORD
	v_pk_fma_f32 v[16:17], v[18:19], s[36:37], 0.5 op_sel_hi:[1,0,0]
	v_lshlrev_b32_e32 v18, 8, v35
	v_cvt_u32_f32_sdwa v16, v16 dst_sel:BYTE_3 dst_unused:UNUSED_PAD src0_sel:DWORD
	v_cvt_u32_f32_sdwa v17, v17 dst_sel:BYTE_3 dst_unused:UNUSED_PAD src0_sel:DWORD
	v_lshlrev_b32_e32 v19, 8, v34
	v_or_b32_e32 v18, v18, v23
	v_or_b32_e32 v19, v19, v22
	v_or_b32_e32 v18, v18, v21
	v_or_b32_e32 v19, v19, v20
	v_or_b32_e32 v17, v18, v17
	v_or_b32_e32 v16, v19, v16
	v_mov_b64_e32 v[238:239], v[16:17]
	global_store_dwordx4 v[32:33], v[236:239], off
	s_nop 1
	v_add_u32_e32 v16, 0xb0, v166
	v_ashrrev_i32_e32 v17, 31, v16
	v_lshlrev_b64 v[18:19], 6, v[16:17]
	v_lshl_add_u64 v[22:23], s[26:27], 0, v[18:19]
	s_mov_b64 s[26:27], -1
	s_cmp_eq_u32 s12, 2
	s_nop 0
	s_nop 0
	s_nop 0
	s_nop 0
	v_mov_b32_e32 v17, v235
	v_fma_f32 v8, v8, v17, v40
	v_mul_f32_e32 v8, 0xbfb8aa3b, v8
	v_fma_f32 v12, v12, v17, v44
	v_exp_f32_e32 v8, v8
	v_mul_f32_e32 v12, 0xbfb8aa3b, v12
	v_exp_f32_e32 v12, v12
; #define PG8_BAR __builtin_amdgcn_s_barrier()
; template <class Epi, class Sched>
; __device__ __forceinline__ void gemm_phase(int wid_s, PG8_LAS unsigned char* lds, const Gemm g, const Sched& S, const Epi& E) {
;     ...
;         if (wr == 0) PG8_BAR;
;         E(acc, cur, wr, wc, fr, fq);
;         if (!has_next) break;
; #pragma unroll
;         for (int a = 0; a < 2; ++a)
; #pragma unroll
;             for (int b = 0; b < 2; ++b)
; #pragma unroll
;                 for (int m = 0; m < 4; ++m)
; #pragma unroll
;                     for (int n = 0; n < 2; ++n) acc[a][b][m][n] = (f32x4){0.f, 0.f, 0.f, 0.f};
;         cur = nxt; cA = nA; cB = nB; ++ui;
;         if (wr == 1) PG8_BAR;
	v_fma_f32 v10, v10, v17, v42
	v_mul_f32_e32 v10, 0xbfb8aa3b, v10
	v_add_f32_e32 v8, 1.0, v8
	v_exp_f32_e32 v10, v10
	v_rcp_f32_e32 v19, v8
	v_fma_f32 v8, v13, v17, v45
	v_fma_f32 v9, v9, v17, v41
	v_add_f32_e32 v12, 1.0, v12
	v_mul_f32_e32 v8, 0xbfb8aa3b, v8
	v_mul_f32_e32 v9, 0xbfb8aa3b, v9
	v_rcp_f32_e32 v18, v12
	v_exp_f32_e32 v8, v8
	v_exp_f32_e32 v9, v9
	v_fma_f32 v12, v14, v17, v46
	v_mul_f32_e32 v12, 0xbfb8aa3b, v12
	v_add_f32_e32 v10, 1.0, v10
	v_fmac_f32_e32 v47, v15, v17
	v_fmac_f32_e32 v43, v11, v17
	v_exp_f32_e32 v12, v12
	v_rcp_f32_e32 v13, v10
	v_mul_f32_e32 v10, 0xbfb8aa3b, v47
	v_mul_f32_e32 v11, 0xbfb8aa3b, v43
	v_exp_f32_e32 v10, v10
	v_exp_f32_e32 v11, v11
	v_add_f32_e32 v8, 1.0, v8
	v_add_f32_e32 v9, 1.0, v9
	v_rcp_f32_e32 v8, v8
	v_rcp_f32_e32 v9, v9
	v_add_f32_e32 v12, 1.0, v12
	v_rcp_f32_e32 v12, v12
	v_add_f32_e32 v10, 1.0, v10
	v_add_f32_e32 v11, 1.0, v11
	v_rcp_f32_e32 v10, v10
	v_rcp_f32_e32 v11, v11
	v_pk_fma_f32 v[8:9], v[8:9], s[36:37], 0.5 op_sel_hi:[1,0,0]
	v_pk_fma_f32 v[14:15], v[18:19], s[36:37], 0.5 op_sel_hi:[1,0,0]
	v_cvt_u32_f32_e32 v18, v8
	v_cvt_u32_f32_e32 v19, v9
	v_cvt_u32_f32_e32 v15, v15
	v_cvt_u32_f32_e32 v14, v14
	v_pk_fma_f32 v[8:9], v[12:13], s[36:37], 0.5 op_sel_hi:[1,0,0]
	v_fma_f32 v0, v0, v17, v24
	v_cvt_u32_f32_sdwa v12, v8 dst_sel:WORD_1 dst_unused:UNUSED_PAD src0_sel:DWORD
	v_cvt_u32_f32_sdwa v13, v9 dst_sel:WORD_1 dst_unused:UNUSED_PAD src0_sel:DWORD
	v_pk_fma_f32 v[8:9], v[10:11], s[36:37], 0.5 op_sel_hi:[1,0,0]
	v_mul_f32_e32 v0, 0xbfb8aa3b, v0
	v_cvt_u32_f32_sdwa v8, v8 dst_sel:BYTE_3 dst_unused:UNUSED_PAD src0_sel:DWORD
	v_cvt_u32_f32_sdwa v9, v9 dst_sel:BYTE_3 dst_unused:UNUSED_PAD src0_sel:DWORD
	v_lshlrev_b32_e32 v10, 8, v19
	v_lshlrev_b32_e32 v11, 8, v18
	v_fma_f32 v4, v4, v17, v28
	v_exp_f32_e32 v0, v0
	v_or_b32_e32 v10, v10, v15
	v_or_b32_e32 v11, v11, v14
	v_mul_f32_e32 v4, 0xbfb8aa3b, v4
	v_or_b32_e32 v10, v10, v13
	v_or_b32_e32 v12, v11, v12
	v_exp_f32_e32 v4, v4
	v_fma_f32 v2, v2, v17, v26
	v_or_b32_e32 v11, v10, v9
	v_or_b32_e32 v10, v12, v8
	v_mad_i64_i32 v[8:9], s[18:19], v16, s28, v[136:137]
	v_mul_f32_e32 v2, 0xbfb8aa3b, v2
	v_lshl_add_u64 v[8:9], v[8:9], 0, v[164:165]
	v_add_f32_e32 v0, 1.0, v0
	v_exp_f32_e32 v2, v2
	v_mov_b64_e32 v[236:237], v[10:11]
	v_mov_b32_e32 v190, v194
	v_mov_b32_e32 v191, 0
	v_lshl_add_u64 v[8:9], v[8:9], 0, v[190:191]
	v_rcp_f32_e32 v11, v0
	v_fma_f32 v0, v5, v17, v29
	v_fma_f32 v1, v1, v17, v25
	v_add_f32_e32 v4, 1.0, v4
	v_mul_f32_e32 v0, 0xbfb8aa3b, v0
	v_mul_f32_e32 v1, 0xbfb8aa3b, v1
	v_rcp_f32_e32 v10, v4
	v_exp_f32_e32 v0, v0
	v_exp_f32_e32 v1, v1
	v_fma_f32 v4, v6, v17, v30
	v_mul_f32_e32 v4, 0xbfb8aa3b, v4
	v_add_f32_e32 v2, 1.0, v2
	v_fmac_f32_e32 v31, v7, v17
	v_fmac_f32_e32 v27, v3, v17
	v_exp_f32_e32 v4, v4
	v_rcp_f32_e32 v5, v2
	v_mul_f32_e32 v2, 0xbfb8aa3b, v31
	v_mul_f32_e32 v3, 0xbfb8aa3b, v27
	v_exp_f32_e32 v2, v2
	v_exp_f32_e32 v3, v3
	v_add_f32_e32 v0, 1.0, v0
	v_add_f32_e32 v1, 1.0, v1
	v_rcp_f32_e32 v0, v0
	v_rcp_f32_e32 v1, v1
	v_add_f32_e32 v4, 1.0, v4
	v_rcp_f32_e32 v4, v4
	v_add_f32_e32 v2, 1.0, v2
	v_add_f32_e32 v3, 1.0, v3
	v_rcp_f32_e32 v2, v2
	v_rcp_f32_e32 v3, v3
	v_pk_fma_f32 v[0:1], v[0:1], s[36:37], 0.5 op_sel_hi:[1,0,0]
	v_pk_fma_f32 v[6:7], v[10:11], s[36:37], 0.5 op_sel_hi:[1,0,0]
	v_cvt_u32_f32_e32 v10, v0
	v_cvt_u32_f32_e32 v11, v1
	v_cvt_u32_f32_e32 v7, v7
	v_cvt_u32_f32_e32 v6, v6
	v_pk_fma_f32 v[0:1], v[4:5], s[36:37], 0.5 op_sel_hi:[1,0,0]
	s_nop 0
	v_cvt_u32_f32_sdwa v4, v0 dst_sel:WORD_1 dst_unused:UNUSED_PAD src0_sel:DWORD
	v_cvt_u32_f32_sdwa v5, v1 dst_sel:WORD_1 dst_unused:UNUSED_PAD src0_sel:DWORD
	v_pk_fma_f32 v[0:1], v[2:3], s[36:37], 0.5 op_sel_hi:[1,0,0]
	v_lshlrev_b32_e32 v2, 8, v11
	v_cvt_u32_f32_sdwa v0, v0 dst_sel:BYTE_3 dst_unused:UNUSED_PAD src0_sel:DWORD
	v_cvt_u32_f32_sdwa v1, v1 dst_sel:BYTE_3 dst_unused:UNUSED_PAD src0_sel:DWORD
	v_lshlrev_b32_e32 v3, 8, v10
	v_or_b32_e32 v2, v2, v7
	v_or_b32_e32 v3, v3, v6
	v_or_b32_e32 v2, v2, v5
	v_or_b32_e32 v3, v3, v4
	v_or_b32_e32 v1, v2, v1
	v_or_b32_e32 v0, v3, v0
	v_mov_b64_e32 v[238:239], v[0:1]
	global_store_dwordx4 v[8:9], v[236:239], off
	s_nop 1
	s_cbranch_scc1 .LBB0_1565
	v_readlane_b32 s18, v254, 58
	v_readlane_b32 s19, v254, 59
	s_andn2_b64 vcc, exec, s[18:19]
	s_cbranch_vccnz .LBB0_1564
	s_barrier
	s_branch .LBB0_1564

.LBB0_1606:
	s_lshr_b64 s[2:3], s[34:35], 10
	s_lshl_b32 s52, s2, 10
	s_ashr_i32 s53, s52, 31
	v_lshl_or_b32 v138, s49, 8, v158
	s_cmp_gt_i32 s2, 0
	v_ashrrev_i32_e32 v139, 31, v138
	s_cselect_b64 s[46:47], -1, 0
	s_lshl_b32 s48, s48, 8
	s_cmp_lt_i32 s2, 1
	v_add_u32_e32 v140, s48, v156
	v_mov_b64_e32 v[154:155], s[14:15]
	s_movk_i32 s3, 0xc00
	v_mad_i64_i32 v[154:155], s[34:35], v140, s3, v[154:155]
	v_lshl_add_u64 v[154:155], v[154:155], 0, s[52:53]
	v_lshl_add_u64 v[154:155], v[154:155], 0, v[138:139]
	v_mov_b32_e32 v240, v140
	v_mov_b32_e32 v241, 0
	v_lshlrev_b64 v[240:241], 10, v[240:241]
	v_lshl_add_u64 v[242:243], v[240:241], 1, v[240:241]
	v_lshl_add_u64 v[242:243], v[242:243], 0, s[14:15]
	v_lshl_add_u64 v[242:243], v[242:243], 0, s[52:53]
	v_lshl_add_u64 v[242:243], v[242:243], 0, v[138:139]
	v_mov_b32_e32 v240, v158
	v_mov_b32_e32 v241, 0
	v_lshl_add_u64 v[242:243], v[242:243], 0, v[240:241]
	global_load_dwordx4 v[192:195], v[242:243], off
	v_add_u32_e32 v240, 16, v140
	v_mov_b32_e32 v241, 0
	v_lshlrev_b64 v[240:241], 10, v[240:241]
	v_lshl_add_u64 v[242:243], v[240:241], 1, v[240:241]
	v_lshl_add_u64 v[242:243], v[242:243], 0, s[14:15]
	v_lshl_add_u64 v[242:243], v[242:243], 0, s[52:53]
	v_lshl_add_u64 v[242:243], v[242:243], 0, v[138:139]
	v_mov_b32_e32 v240, v158
	v_mov_b32_e32 v241, 0
	v_lshl_add_u64 v[242:243], v[242:243], 0, v[240:241]
	global_load_dwordx4 v[196:199], v[242:243], off
	v_add_u32_e32 v240, 32, v140
	v_mov_b32_e32 v241, 0
	v_lshlrev_b64 v[240:241], 10, v[240:241]
	v_lshl_add_u64 v[242:243], v[240:241], 1, v[240:241]
	v_lshl_add_u64 v[242:243], v[242:243], 0, s[14:15]
	v_lshl_add_u64 v[242:243], v[242:243], 0, s[52:53]
	v_lshl_add_u64 v[242:243], v[242:243], 0, v[138:139]
	v_mov_b32_e32 v240, v158
	v_mov_b32_e32 v241, 0
	v_lshl_add_u64 v[242:243], v[242:243], 0, v[240:241]
	global_load_dwordx4 v[200:203], v[242:243], off
	v_add_u32_e32 v240, 48, v140
	v_mov_b32_e32 v241, 0
	v_lshlrev_b64 v[240:241], 10, v[240:241]
	v_lshl_add_u64 v[242:243], v[240:241], 1, v[240:241]
	v_lshl_add_u64 v[242:243], v[242:243], 0, s[14:15]
	v_lshl_add_u64 v[242:243], v[242:243], 0, s[52:53]
	v_lshl_add_u64 v[242:243], v[242:243], 0, v[138:139]
	v_mov_b32_e32 v240, v158
	v_mov_b32_e32 v241, 0
	v_lshl_add_u64 v[242:243], v[242:243], 0, v[240:241]
	global_load_dwordx4 v[204:207], v[242:243], off
	s_cbranch_scc1 .Lmy_pj_skipA
	v_mov_b32_e32 v240, v140
	v_mov_b32_e32 v241, 0
	v_lshlrev_b64 v[240:241], 10, v[240:241]
	v_lshl_add_u64 v[166:167], v[240:241], 0, v[138:139]
	v_lshl_add_u64 v[166:167], v[166:167], 1, s[16:17]
	global_load_dwordx4 v[208:211], v[166:167], off
	global_load_dwordx4 v[212:215], v[166:167], off offset:256
	v_add_u32_e32 v240, 16, v140
	v_mov_b32_e32 v241, 0
	v_lshlrev_b64 v[240:241], 10, v[240:241]
	v_lshl_add_u64 v[166:167], v[240:241], 0, v[138:139]
	v_lshl_add_u64 v[166:167], v[166:167], 1, s[16:17]
	global_load_dwordx4 v[216:219], v[166:167], off
	global_load_dwordx4 v[220:223], v[166:167], off offset:256
	v_add_u32_e32 v240, 32, v140
	v_mov_b32_e32 v241, 0
	v_lshlrev_b64 v[240:241], 10, v[240:241]
	v_lshl_add_u64 v[166:167], v[240:241], 0, v[138:139]
	v_lshl_add_u64 v[166:167], v[166:167], 1, s[16:17]
	global_load_dwordx4 v[224:227], v[166:167], off
	global_load_dwordx4 v[228:231], v[166:167], off offset:256
	v_add_u32_e32 v240, 48, v140
	v_mov_b32_e32 v241, 0
	v_lshlrev_b64 v[240:241], 10, v[240:241]
	v_lshl_add_u64 v[166:167], v[240:241], 0, v[138:139]
	v_lshl_add_u64 v[166:167], v[166:167], 1, s[16:17]
	global_load_dwordx4 v[232:235], v[166:167], off
	global_load_dwordx4 v[236:239], v[166:167], off offset:256

.LBB0_1622:
	v_cvt_pk_bf16_f32 v68, v68, v69
	v_cvt_pk_bf16_f32 v69, v70, v71
	v_cvt_pk_bf16_f32 v70, v64, v65
	v_cvt_pk_bf16_f32 v71, v66, v67
	global_store_dwordx4 v[72:73], v[68:71], off offset:256
	s_nop 1
	v_add_u32_e32 v240, 128, v140
	v_mov_b32_e32 v241, 0
	v_lshlrev_b64 v[240:241], 10, v[240:241]
	v_lshl_add_u64 v[242:243], v[240:241], 1, v[240:241]
	v_lshl_add_u64 v[242:243], v[242:243], 0, s[14:15]
	v_lshl_add_u64 v[242:243], v[242:243], 0, s[52:53]
	v_lshl_add_u64 v[242:243], v[242:243], 0, v[138:139]
	v_mov_b32_e32 v240, v158
	v_mov_b32_e32 v241, 0
	v_lshl_add_u64 v[242:243], v[242:243], 0, v[240:241]
	global_load_dwordx4 v[192:195], v[242:243], off
	v_add_u32_e32 v240, 144, v140
	v_mov_b32_e32 v241, 0
	v_lshlrev_b64 v[240:241], 10, v[240:241]
	v_lshl_add_u64 v[242:243], v[240:241], 1, v[240:241]
	v_lshl_add_u64 v[242:243], v[242:243], 0, s[14:15]
	v_lshl_add_u64 v[242:243], v[242:243], 0, s[52:53]
	v_lshl_add_u64 v[242:243], v[242:243], 0, v[138:139]
	v_mov_b32_e32 v240, v158
	v_mov_b32_e32 v241, 0
	v_lshl_add_u64 v[242:243], v[242:243], 0, v[240:241]
	global_load_dwordx4 v[196:199], v[242:243], off
	v_add_u32_e32 v240, 160, v140
	v_mov_b32_e32 v241, 0
	v_lshlrev_b64 v[240:241], 10, v[240:241]
	v_lshl_add_u64 v[242:243], v[240:241], 1, v[240:241]
	v_lshl_add_u64 v[242:243], v[242:243], 0, s[14:15]
	v_lshl_add_u64 v[242:243], v[242:243], 0, s[52:53]
	v_lshl_add_u64 v[242:243], v[242:243], 0, v[138:139]
	v_mov_b32_e32 v240, v158
	v_mov_b32_e32 v241, 0
	v_lshl_add_u64 v[242:243], v[242:243], 0, v[240:241]
	global_load_dwordx4 v[200:203], v[242:243], off
	v_add_u32_e32 v240, 176, v140
	v_mov_b32_e32 v241, 0
	v_lshlrev_b64 v[240:241], 10, v[240:241]
	v_lshl_add_u64 v[242:243], v[240:241], 1, v[240:241]
	v_lshl_add_u64 v[242:243], v[242:243], 0, s[14:15]
	v_lshl_add_u64 v[242:243], v[242:243], 0, s[52:53]
	v_lshl_add_u64 v[242:243], v[242:243], 0, v[138:139]
	v_mov_b32_e32 v240, v158
	v_mov_b32_e32 v241, 0
	v_lshl_add_u64 v[242:243], v[242:243], 0, v[240:241]
	global_load_dwordx4 v[204:207], v[242:243], off
	s_and_b64 vcc, exec, s[2:3]
	s_cbranch_vccnz .Lmy_pj_skipB
	v_add_u32_e32 v240, 128, v140
	v_mov_b32_e32 v241, 0
	v_lshlrev_b64 v[240:241], 10, v[240:241]
	v_lshl_add_u64 v[166:167], v[240:241], 0, v[138:139]
	v_lshl_add_u64 v[166:167], v[166:167], 1, s[16:17]
	global_load_dwordx4 v[208:211], v[166:167], off
	global_load_dwordx4 v[212:215], v[166:167], off offset:256
	v_add_u32_e32 v240, 144, v140
	v_mov_b32_e32 v241, 0
	v_lshlrev_b64 v[240:241], 10, v[240:241]
	v_lshl_add_u64 v[166:167], v[240:241], 0, v[138:139]
	v_lshl_add_u64 v[166:167], v[166:167], 1, s[16:17]
	global_load_dwordx4 v[216:219], v[166:167], off
	global_load_dwordx4 v[220:223], v[166:167], off offset:256
	v_add_u32_e32 v240, 160, v140
	v_mov_b32_e32 v241, 0
	v_lshlrev_b64 v[240:241], 10, v[240:241]
	v_lshl_add_u64 v[166:167], v[240:241], 0, v[138:139]
	v_lshl_add_u64 v[166:167], v[166:167], 1, s[16:17]
	global_load_dwordx4 v[224:227], v[166:167], off
	global_load_dwordx4 v[228:231], v[166:167], off offset:256
	v_add_u32_e32 v240, 176, v140
	v_mov_b32_e32 v241, 0
	v_lshlrev_b64 v[240:241], 10, v[240:241]
	v_lshl_add_u64 v[166:167], v[240:241], 0, v[138:139]
	v_lshl_add_u64 v[166:167], v[166:167], 1, s[16:17]
	global_load_dwordx4 v[232:235], v[166:167], off
	global_load_dwordx4 v[236:239], v[166:167], off offset:256
